# strategy 4: static s_setprio 1 for waves 4-7 during the attention phase, on top of the snake-order attention
# baseline (speedup 1.0000x reference)
; #define LAS __attribute__((address_space(3)))
; template <int KIND> __device__ __forceinline__ void attn_dma(unsigned dst, const bf16_t* src, const AttnUnit& u, int wid, int lane) {
;     const int np = u.nrows * 5;
;     const char* base = (const char*)(src + ((size_t)(u.b * NHEAD + u.h) * SEQ + u.krow_lo * 64 + 24 * u.jh) * HD);
; #pragma unroll
;     for (int it = 0; it < 10; ++it) {
;         const int pi = it * 8 + wid;
;         if (pi < np) {
;             const int w = (pi * 205) >> 10, p = pi - 5 * w, c = 8 * p + (lane >> 3);
;             const int sw = (KIND == 0) ? (((c >> 1) & 1) | (((c >> 3) & 3) << 1)) : ((((c >> 1) & 1) << 1) | (((c >> 3) & 1) << 2));
;             const int ch = (lane & 7) ^ sw;
;             const char* gp = base + (w * 64 + c) * (HD * 2) + ch * 16;
;             glds16(gp, (unsigned)__builtin_amdgcn_readfirstlane(dst + pi * 1024));
;         }
;     }
; }
; __device__ __forceinline__ void p2_attention(Frame& F, const bf16_t* Qg, const bf16_t* Kg, const bf16_t* Vg, bf16_t* MIX) {
;     const int lane = F.lane, wid = F.wave;
;     LAS unsigned char* lds = F.lds;
;     const unsigned lds0 = (unsigned)(size_t)F.lds;
;     const int q = lane & 15, g = lane >> 4;
;     constexpr int NUNITS = BATCH * NHEAD * 16, UW = 8;
;     for (int uidx = F.vcu * UW; uidx < NUNITS; uidx += F.G * UW) {
;         const int h = (uidx >> 4) & 7;
;         __syncthreads();
;         {   LAS float* tab = (LAS float*)(lds + AT_TAB);
;             for (int i = F.tid; i < 15 * 64; i += NWAVES * 64) { const int rr = i >> 6, cc = (i & 63) - 16; tab[i] = (cc >= 0 && cc < 31) ? F.rpb[h * 465 + rr * 31 + cc] * LOG2E : 0.f; } }
;         AttnUnit u = attn_decode(uidx);
.LBB0_263:
	s_cmp_eq_u32 s98, 2
	s_cbranch_scc1 .LBB0_336
	s_cmpk_gt_i32 s86, 0xff
	s_cbranch_scc1 .LBB0_336
	s_cmp_lt_u32 s85, 4
	s_cbranch_scc1 .Latt_prio_skip
	s_setprio 1
.Latt_prio_skip:
	s_mov_b32 s100, 0
	s_cmp_ge_u32 s85, 5
	s_cselect_b32 s1, 5, 0
	s_sub_i32 s0, s85, s1
	s_cmp_ge_u32 s0, 3
	s_cselect_b32 s1, 0x1, 0
	s_or_b32 s100, s100, s1
	s_cmp_le_u32 s0, 1
	s_cselect_b32 s1, 0x10000, 0
	s_or_b32 s100, s100, s1
	s_add_i32 s0, s0, 3
	s_cmp_ge_u32 s0, 5
	s_cselect_b32 s1, 5, 0
	s_sub_i32 s0, s0, s1
	s_cmp_ge_u32 s0, 3
	s_cselect_b32 s1, 0x2, 0
	s_or_b32 s100, s100, s1
	s_cmp_le_u32 s0, 1
	s_cselect_b32 s1, 0x20000, 0
	s_or_b32 s100, s100, s1
	s_add_i32 s0, s0, 3
	s_cmp_ge_u32 s0, 5
	s_cselect_b32 s1, 5, 0
	s_sub_i32 s0, s0, s1
	s_cmp_ge_u32 s0, 3
	s_cselect_b32 s1, 0x4, 0
	s_or_b32 s100, s100, s1
	s_cmp_le_u32 s0, 1
	s_cselect_b32 s1, 0x40000, 0
	s_or_b32 s100, s100, s1
	s_add_i32 s0, s0, 3
	s_cmp_ge_u32 s0, 5
	s_cselect_b32 s1, 5, 0
	s_sub_i32 s0, s0, s1
	s_cmp_ge_u32 s0, 3
	s_cselect_b32 s1, 0x8, 0
	s_or_b32 s100, s100, s1
	s_cmp_le_u32 s0, 1
	s_cselect_b32 s1, 0x80000, 0
	s_or_b32 s100, s100, s1
	s_add_i32 s0, s0, 3
	s_cmp_ge_u32 s0, 5
	s_cselect_b32 s1, 5, 0
	s_sub_i32 s0, s0, s1
	s_cmp_ge_u32 s0, 3
	s_cselect_b32 s1, 0x10, 0
	s_or_b32 s100, s100, s1
	s_cmp_le_u32 s0, 1
	s_cselect_b32 s1, 0x100000, 0
	s_or_b32 s100, s100, s1
	s_add_i32 s0, s0, 3
	s_cmp_ge_u32 s0, 5
	s_cselect_b32 s1, 5, 0
	s_sub_i32 s0, s0, s1
	s_cmp_ge_u32 s0, 3
	s_cselect_b32 s1, 0x20, 0
	s_or_b32 s100, s100, s1
	s_cmp_le_u32 s0, 1
	s_cselect_b32 s1, 0x200000, 0
	s_or_b32 s100, s100, s1
	s_add_i32 s0, s0, 3
	s_cmp_ge_u32 s0, 5
	s_cselect_b32 s1, 5, 0
	s_sub_i32 s0, s0, s1
	s_cmp_ge_u32 s0, 3
	s_cselect_b32 s1, 0x40, 0
	s_or_b32 s100, s100, s1
	s_cmp_le_u32 s0, 1
	s_cselect_b32 s1, 0x400000, 0
	s_or_b32 s100, s100, s1
	s_add_i32 s0, s0, 3
	s_cmp_ge_u32 s0, 5
	s_cselect_b32 s1, 5, 0
	s_sub_i32 s0, s0, s1
	s_cmp_ge_u32 s0, 3
	s_cselect_b32 s1, 0x80, 0
	s_or_b32 s100, s100, s1
	s_cmp_le_u32 s0, 1
	s_cselect_b32 s1, 0x800000, 0
	s_or_b32 s100, s100, s1
	s_add_i32 s0, s0, 3
	s_cmp_ge_u32 s0, 5
	s_cselect_b32 s1, 5, 0
	s_sub_i32 s0, s0, s1
	s_cmp_ge_u32 s0, 3
	s_cselect_b32 s1, 0x100, 0
	s_or_b32 s100, s100, s1
	s_cmp_le_u32 s0, 1
	s_cselect_b32 s1, 0x1000000, 0
	s_or_b32 s100, s100, s1
	s_add_i32 s0, s0, 3
	s_cmp_ge_u32 s0, 5
	s_cselect_b32 s1, 5, 0
	s_sub_i32 s0, s0, s1
	s_cmp_ge_u32 s0, 3
	s_cselect_b32 s1, 0x200, 0
	s_or_b32 s100, s100, s1
	s_cmp_le_u32 s0, 1
	s_cselect_b32 s1, 0x2000000, 0
	s_or_b32 s100, s100, s1
	s_add_i32 s0, s0, 3
	s_cmp_ge_u32 s0, 5
	s_cselect_b32 s1, 5, 0
	s_sub_i32 s0, s0, s1
	s_add_u32 s22, s28, 0x12000000
	s_addc_u32 s23, s29, 0
	s_add_u32 s40, s28, 0xe000000
	s_addc_u32 s41, s29, 0
	s_and_b32 s0, s33, 0xffffffc0
	v_add_u32_e32 v99, s0, v166
	s_mul_i32 s0, s85, 0xcd
	s_lshr_b32 s1, s0, 10
	s_mul_i32 s4, s1, -5
	v_ashrrev_i32_e32 v2, 3, v166
	s_add_i32 s4, s4, s85
	v_lshl_add_u32 v4, s4, 3, v2
	s_add_i32 s4, s0, 0x668
	s_lshr_b32 s4, s4, 10
	s_add_i32 s43, s85, 8
	s_mul_i32 s5, s4, -5
	s_add_i32 s5, s5, s43
	v_lshl_add_u32 v5, s5, 3, v2
	s_add_i32 s5, s0, 0xcd0
	s_lshr_b32 s5, s5, 10
	s_add_i32 s48, s85, 16
	s_mul_i32 s6, s5, -5
	s_add_i32 s6, s6, s48
	v_lshl_add_u32 v6, s6, 3, v2
	s_add_i32 s6, s0, 0x1338
	v_lshrrev_b32_e32 v1, 2, v4
	s_lshr_b32 s6, s6, 10
	v_bfe_u32 v0, v2, 1, 1
	v_and_b32_e32 v3, 7, v166
	v_and_b32_e32 v1, 6, v1
	s_add_i32 s50, s85, 24
	s_mul_i32 s7, s6, -5
	v_bitop3_b32 v1, v1, v3, v0 bitop3:0x36
	s_add_i32 s7, s7, s50
	v_lshlrev_b32_e32 v102, 4, v1
	v_lshrrev_b32_e32 v1, 2, v5
	v_lshl_add_u32 v7, s7, 3, v2
	s_add_i32 s7, s0, 0x19a0
	v_and_b32_e32 v1, 6, v1
	s_lshr_b32 s7, s7, 10
	v_bitop3_b32 v1, v1, v3, v0 bitop3:0x36
	s_add_i32 s54, s85, 32
	s_mul_i32 s8, s7, -5
	v_lshlrev_b32_e32 v106, 4, v1
	v_lshrrev_b32_e32 v1, 2, v6
	s_add_i32 s8, s8, s54
	v_and_b32_e32 v1, 6, v1
	v_lshl_add_u32 v8, s8, 3, v2
	s_add_i32 s8, s0, 0x2008
	v_bitop3_b32 v1, v1, v3, v0 bitop3:0x36
	s_lshr_b32 s8, s8, 10
	v_lshlrev_b32_e32 v110, 4, v1
	v_lshrrev_b32_e32 v1, 2, v7
	s_add_i32 s64, s85, 40
	s_mul_i32 s9, s8, -5
	v_and_b32_e32 v1, 6, v1
	s_add_i32 s9, s9, s64
	v_bitop3_b32 v1, v1, v3, v0 bitop3:0x36
	v_lshl_add_u32 v9, s9, 3, v2
	s_add_i32 s9, s0, 0x2670
	v_lshlrev_b32_e32 v114, 4, v1
	v_lshrrev_b32_e32 v1, 2, v8
	s_lshr_b32 s9, s9, 10
	v_and_b32_e32 v1, 6, v1
	s_add_i32 s66, s85, 48
	s_mul_i32 s10, s9, -5
	v_bitop3_b32 v1, v1, v3, v0 bitop3:0x36
	s_add_i32 s10, s10, s66
	v_lshlrev_b32_e32 v118, 4, v1
	v_lshrrev_b32_e32 v1, 2, v9
	v_lshl_add_u32 v10, s10, 3, v2
	s_add_i32 s10, s0, 0x2cd8
	v_and_b32_e32 v1, 6, v1
	s_lshr_b32 s10, s10, 10
	v_bitop3_b32 v1, v1, v3, v0 bitop3:0x36
	s_add_i32 s68, s85, 56
	s_mul_i32 s11, s10, -5
	v_lshlrev_b32_e32 v122, 4, v1
	v_lshrrev_b32_e32 v1, 2, v10
	s_add_i32 s11, s11, s68
	v_and_b32_e32 v1, 6, v1
	v_lshl_add_u32 v11, s11, 3, v2
	s_add_i32 s11, s0, 0x3340
	v_bitop3_b32 v1, v1, v3, v0 bitop3:0x36
	s_lshr_b32 s11, s11, 10
	v_lshlrev_b32_e32 v126, 4, v1
	v_lshrrev_b32_e32 v1, 2, v11
	s_add_i32 s70, s85, 64
	s_mul_i32 s12, s11, -5
	v_and_b32_e32 v1, 6, v1
	s_add_i32 s12, s12, s70
	s_addk_i32 s0, 0x39a8
	v_bitop3_b32 v1, v1, v3, v0 bitop3:0x36
	v_lshl_add_u32 v12, s12, 3, v2
	s_lshr_b32 s0, s0, 10
	v_lshlrev_b32_e32 v130, 4, v1
	v_lshrrev_b32_e32 v1, 2, v12
	s_add_i32 s72, s85, 0x48
	s_mul_i32 s12, s0, -5
	v_and_b32_e32 v1, 6, v1
	s_add_i32 s12, s12, s72
	v_bitop3_b32 v1, v1, v3, v0 bitop3:0x36
	v_lshl_add_u32 v13, s12, 3, v2
	v_lshlrev_b32_e32 v134, 4, v1
	v_lshrrev_b32_e32 v1, 2, v13
	v_and_b32_e32 v1, 6, v1
	v_bitop3_b32 v0, v1, v3, v0 bitop3:0x36
	v_lshlrev_b32_e32 v138, 4, v0
; template <int KIND> __device__ __forceinline__ void attn_dma(unsigned dst, const bf16_t* src, const AttnUnit& u, int wid, int lane) {
;     const int np = u.nrows * 5;
;     const char* base = (const char*)(src + ((size_t)(u.b * NHEAD + u.h) * SEQ + u.krow_lo * 64 + 24 * u.jh) * HD);
; #pragma unroll
;     for (int it = 0; it < 10; ++it) {
;         const int pi = it * 8 + wid;
;         if (pi < np) {
;             const int w = (pi * 205) >> 10, p = pi - 5 * w, c = 8 * p + (lane >> 3);
;             const int sw = (KIND == 0) ? (((c >> 1) & 1) | (((c >> 3) & 3) << 1)) : ((((c >> 1) & 1) << 1) | (((c >> 3) & 1) << 2));
;             const int ch = (lane & 7) ^ sw;
;             const char* gp = base + (w * 64 + c) * (HD * 2) + ch * 16;
;             glds16(gp, (unsigned)__builtin_amdgcn_readfirstlane(dst + pi * 1024));
;         }
;     }
; }
; __device__ __forceinline__ void p2_attention(Frame& F, const bf16_t* Qg, const bf16_t* Kg, const bf16_t* Vg, bf16_t* MIX) {
;     const int lane = F.lane, wid = F.wave;
;     LAS unsigned char* lds = F.lds;
;     const unsigned lds0 = (unsigned)(size_t)F.lds;
;     const int q = lane & 15, g = lane >> 4;
;     constexpr int NUNITS = BATCH * NHEAD * 16, UW = 8;
;     for (int uidx = F.vcu * UW; uidx < NUNITS; uidx += F.G * UW) {
;         const int h = (uidx >> 4) & 7;
;         __syncthreads();
;         {   LAS float* tab = (LAS float*)(lds + AT_TAB);
;             for (int i = F.tid; i < 15 * 64; i += NWAVES * 64) { const int rr = i >> 6, cc = (i & 63) - 16; tab[i] = (cc >= 0 && cc < 31) ? F.rpb[h * 465 + rr * 31 + cc] * LOG2E : 0.f; } }
;         AttnUnit u = attn_decode(uidx);
;         attn_dma<0>(lds0 + AT_A, Kg, u, wid, lane);
;         bf16x8 qf[2][2];
; #pragma unroll
;         for (int jb = 0; jb < 2; ++jb) { const bf16_t* qp = Qg + ((size_t)(u.b * NHEAD + u.h) * SEQ + (u.r0 + wid) * 64 + 32 * u.jh + 16 * jb + q) * HD + 8 * g; qf[jb][0] = __builtin_nontemporal_load((const bf16x8*)qp); qf[jb][1] = __builtin_nontemporal_load((const bf16x8*)(qp + 32)); }
;         ATT_WAIT_BAR();
;         for (int ui = 0; ui < UW; ++ui) {
;             asm volatile("" : "+v"(qf[0][0]), "+v"(qf[0][1]), "+v"(qf[1][0]), "+v"(qf[1][1]));
;             attn_dma<1>(lds0 + AT_B, Vg, u, wid, lane);
;             const int r = u.r0 + wid, rs = rs_of(r), wbase = rs - u.krow_lo;
;             u32x4 pw[2][8]; float il[2];
	v_lshlrev_b32_e32 v0, 3, v169
	v_ashrrev_i32_e32 v1, 31, v0
	v_lshl_add_u64 v[140:141], v[0:1], 1, s[36:37]
	v_and_b32_e32 v1, 2, v2
	v_lshrrev_b32_e32 v2, 1, v4
	v_and_b32_e32 v2, 4, v2
	v_bitop3_b32 v2, v2, v3, v1 bitop3:0x36
	v_lshlrev_b32_e32 v142, 4, v2
	v_lshrrev_b32_e32 v2, 1, v5
	v_and_b32_e32 v2, 4, v2
	v_bitop3_b32 v2, v2, v3, v1 bitop3:0x36
	v_lshlrev_b32_e32 v144, 4, v2
	v_lshrrev_b32_e32 v2, 1, v6
	v_and_b32_e32 v2, 4, v2
	v_bitop3_b32 v2, v2, v3, v1 bitop3:0x36
	v_lshlrev_b32_e32 v146, 4, v2
	v_lshrrev_b32_e32 v2, 1, v7
	v_and_b32_e32 v2, 4, v2
	v_bitop3_b32 v2, v2, v3, v1 bitop3:0x36
	v_lshlrev_b32_e32 v148, 4, v2
	v_lshrrev_b32_e32 v2, 1, v8
	v_and_b32_e32 v2, 4, v2
	v_bitop3_b32 v2, v2, v3, v1 bitop3:0x36
	v_lshlrev_b32_e32 v150, 4, v2
	v_lshrrev_b32_e32 v2, 1, v9
	v_and_b32_e32 v2, 4, v2
	v_bitop3_b32 v2, v2, v3, v1 bitop3:0x36
	v_lshlrev_b32_e32 v152, 4, v2
	v_lshrrev_b32_e32 v2, 1, v10
	v_and_b32_e32 v2, 4, v2
	v_bitop3_b32 v2, v2, v3, v1 bitop3:0x36
	v_lshlrev_b32_e32 v154, 4, v2
	v_lshrrev_b32_e32 v2, 1, v11
	v_and_b32_e32 v2, 4, v2
	v_bitop3_b32 v2, v2, v3, v1 bitop3:0x36
	v_lshlrev_b32_e32 v156, 4, v2
	v_lshrrev_b32_e32 v2, 1, v12
	v_and_b32_e32 v2, 4, v2
	v_bitop3_b32 v2, v2, v3, v1 bitop3:0x36
	v_lshlrev_b32_e32 v158, 4, v2
	v_lshrrev_b32_e32 v2, 1, v13
	v_and_b32_e32 v2, 4, v2
	v_bitop3_b32 v1, v2, v3, v1 bitop3:0x36
	s_lshl_b32 s4, s4, 13
	v_lshlrev_b32_e32 v160, 4, v1
	v_bfe_u32 v164, v166, 2, 2
	v_and_b32_e32 v1, 3, v166
	v_add_u32_e32 v170, 8, v0
	v_lshrrev_b32_e32 v0, 2, v166
	v_lshl_add_u32 v104, v5, 7, s4
	s_lshl_b32 s5, s5, 13
	s_add_i32 s12, 0, 0x12c00
	v_lshl_or_b32 v165, v164, 3, v1
	v_and_b32_e32 v5, 2, v0
	v_and_b32_e32 v0, 16, v96
	v_and_b32_e32 v1, 8, v96
	v_lshl_add_u32 v108, v6, 7, s5
	v_add3_u32 v6, s12, v0, v1
	v_lshlrev_b32_e32 v0, 6, v166
	v_mov_b32_e32 v97, 0
	v_and_b32_e32 v96, 0x3c0, v0
	v_and_b32_e32 v2, -16, v166
	s_lshl_b32 s1, s1, 13
	v_lshl_add_u64 v[0:1], s[24:25], 0, v[96:97]
	v_ashrrev_i32_e32 v3, 31, v2
	v_lshl_add_u32 v100, v4, 7, s1
	v_bfe_u32 v4, v166, 1, 1
	v_lshl_add_u64 v[162:163], v[0:1], 0, v[2:3]
	v_lshlrev_b32_e32 v0, 1, v164
	v_bitop3_b32 v1, v0, v169, v4 bitop3:0x36
	v_add_u32_e32 v0, 2, v0
	v_and_b32_e32 v0, 6, v0
	v_bitop3_b32 v0, v0, v169, v4 bitop3:0x36
	v_lshlrev_b32_e32 v173, 4, v0
	v_lshlrev_b32_e32 v0, 2, v169
	v_and_or_b32 v0, v0, 4, v5
	v_lshlrev_b32_e32 v176, 4, v0
	v_add_u32_e32 v0, 1, v169
	v_lshlrev_b32_e32 v171, 4, v1
	v_lshlrev_b32_e32 v1, 2, v0
	v_and_or_b32 v1, v1, 4, v5
	v_and_b32_e32 v185, 63, v166
	s_lshl_b32 s4, s43, 10
	s_lshl_b32 s5, s48, 10
	v_lshl_add_u32 v180, v0, 10, v6
	v_lshlrev_b32_e32 v181, 4, v1
	v_add_u32_e32 v0, -16, v185
	v_and_b32_e32 v1, 64, v168
	s_add_i32 s45, s4, 0
	s_add_i32 s49, s5, 0
	s_lshl_b32 s0, s0, 13
	s_add_i32 s37, s4, s12
	s_add_i32 s74, s5, s12
	v_cmp_gt_u32_e64 s[4:5], 31, v0
	v_xor_b32_e32 v0, 16, v168
	v_add_u32_e32 v1, 64, v1
	v_lshl_add_u32 v136, v13, 7, s0
	s_lshl_b32 s0, s72, 10
	v_cmp_lt_i32_e32 vcc, v0, v1
	s_lshl_b32 s1, s85, 10
	s_add_i32 s73, s0, 0
	s_add_i32 s81, s0, s12
	s_movk_i32 s0, 0x3c0
	v_cndmask_b32_e32 v0, v168, v0, vcc
	s_add_i32 s42, s1, 0
	s_add_i32 s36, s1, s12
	v_cmp_gt_i32_e64 s[20:21], s0, v99
	v_lshlrev_b32_e32 v186, 2, v0
	v_xor_b32_e32 v0, 32, v168
	s_add_i32 s0, 0, 0x25800
	s_lshl_b32 s1, s85, 8
	s_lshl_b32 s6, s6, 13
	s_lshl_b32 s7, s7, 13
	s_lshl_b32 s8, s8, 13
	s_lshl_b32 s9, s9, 13
	s_lshl_b32 s10, s10, 13
	s_lshl_b32 s11, s11, 13
	v_lshl_add_u32 v175, v169, 10, v6
	v_cmp_lt_i32_e32 vcc, v0, v1
	v_lshl_add_u32 v169, v169, 5, s0
	s_add_i32 s0, s0, s1
	v_and_b32_e32 v98, 15, v166
	v_lshl_add_u32 v112, v7, 7, s6
	s_lshl_b32 s6, s50, 10
	v_lshl_add_u32 v116, v8, 7, s7
	s_lshl_b32 s7, s54, 10
	v_lshl_add_u32 v120, v9, 7, s8
	s_lshl_b32 s8, s64, 10
	v_lshl_add_u32 v124, v10, 7, s9
	s_lshl_b32 s9, s66, 10
	v_lshl_add_u32 v128, v11, 7, s10
	s_lshl_b32 s10, s68, 10
	v_lshl_add_u32 v132, v12, 7, s11
	s_lshl_b32 s11, s70, 10
	v_cndmask_b32_e32 v0, v168, v0, vcc
	v_lshl_add_u32 v166, v166, 2, s0
	s_lshl_b32 s0, s86, 5
	v_ashrrev_i32_e32 v101, 31, v100
	v_mov_b32_e32 v103, v97
	v_ashrrev_i32_e32 v105, 31, v104
	v_mov_b32_e32 v107, v97
	v_ashrrev_i32_e32 v109, 31, v108
	v_mov_b32_e32 v111, v97
	v_ashrrev_i32_e32 v113, 31, v112
	v_mov_b32_e32 v115, v97
	s_add_i32 s51, s6, 0
	v_ashrrev_i32_e32 v117, 31, v116
	v_mov_b32_e32 v119, v97
	s_add_i32 s55, s7, 0
	v_ashrrev_i32_e32 v121, 31, v120
	v_mov_b32_e32 v123, v97
	s_add_i32 s65, s8, 0
	v_ashrrev_i32_e32 v125, 31, v124
	v_mov_b32_e32 v127, v97
	s_add_i32 s67, s9, 0
	v_ashrrev_i32_e32 v129, 31, v128
	v_mov_b32_e32 v131, v97
	s_add_i32 s69, s10, 0
	v_ashrrev_i32_e32 v133, 31, v132
	v_mov_b32_e32 v135, v97
	s_add_i32 s71, s11, 0
	v_ashrrev_i32_e32 v137, 31, v136
	v_mov_b32_e32 v139, v97
	v_mov_b32_e32 v143, v97
	v_mov_b32_e32 v145, v97
	v_mov_b32_e32 v147, v97
	v_mov_b32_e32 v149, v97
	s_add_i32 s75, s6, s12
	v_mov_b32_e32 v151, v97
	s_add_i32 s76, s7, s12
	v_mov_b32_e32 v153, v97
	s_add_i32 s77, s8, s12
	v_mov_b32_e32 v155, v97
	s_add_i32 s78, s9, s12
	v_mov_b32_e32 v157, v97
	s_add_i32 s79, s10, s12
	v_mov_b32_e32 v159, v97
	s_add_i32 s80, s11, s12
	v_mov_b32_e32 v161, v97
	v_xor_b32_e32 v172, 64, v171
	v_xor_b32_e32 v174, 64, v173
	v_xor_b32_e32 v177, 32, v176
	v_xor_b32_e32 v178, 64, v176
	v_xor_b32_e32 v179, 0x60, v176
	v_xor_b32_e32 v182, 32, v181
	v_xor_b32_e32 v183, 64, v181
	v_xor_b32_e32 v184, 0x60, v181
	s_lshl_b32 s82, s3, 3
	v_lshlrev_b32_e32 v168, 2, v0
	s_or_b32 s83, s0, 4
	s_lshl_b32 s86, s3, 5
	s_movk_i32 s87, 0x1bf
	s_mov_b32 s88, 0xff800000
	v_mov_b32_e32 v187, 0xff800000
	s_branch .LBB0_266

; __device__ __forceinline__ void p2_attention(Frame& F, const bf16_t* Qg, const bf16_t* Kg, const bf16_t* Vg, bf16_t* MIX) {
;     ...
;         }
;     }
; }
.LBB0_336:
	s_setprio 0
	s_cmp_lg_u32 s98, 1
	s_cbranch_scc1 .Lp2_end
	s_mov_b32 s98, 2
	s_mov_b32 s86, s99
	s_branch .Lp2_setup
